# lever 1/8 (counted waits + LDS/MFMA overlap) on the S5 output block GEMM: B-fragment ds_reads issued 8 MFMAs ahead into fresh VGPR quads with counted lgkmcnt instead of ds_read -> lgkmcnt(0) -> MFMA 6
# speedup vs baseline: 1.0036x; 1.0012x over previous
.LBB0_960:
	v_add_u32_e32 v2, -14, v66
	v_ashrrev_i32_e32 v3, 31, v2
	v_lshlrev_b64 v[2:3], 9, v[2:3]
	v_lshl_add_u64 v[2:3], v[62:63], 0, v[2:3]
	global_load_dwordx4 v[74:77], v[2:3], off
	v_add_u32_e32 v2, -12, v66
	v_ashrrev_i32_e32 v3, 31, v2
	v_lshlrev_b64 v[2:3], 9, v[2:3]
	v_lshl_add_u64 v[2:3], v[62:63], 0, v[2:3]
	global_load_dwordx4 v[58:61], v[2:3], off
	v_add_u32_e32 v2, -10, v66
	v_ashrrev_i32_e32 v3, 31, v2
	v_lshlrev_b64 v[2:3], 9, v[2:3]
	v_lshl_add_u64 v[2:3], v[62:63], 0, v[2:3]
	global_load_dwordx4 v[54:57], v[2:3], off
	v_add_u32_e32 v2, -8, v66
	v_ashrrev_i32_e32 v3, 31, v2
	v_lshlrev_b64 v[2:3], 9, v[2:3]
	v_lshl_add_u64 v[2:3], v[62:63], 0, v[2:3]
	global_load_dwordx4 v[46:49], v[2:3], off
	v_add_u32_e32 v2, -6, v66
	v_ashrrev_i32_e32 v3, 31, v2
	v_lshlrev_b64 v[2:3], 9, v[2:3]
	v_lshl_add_u64 v[2:3], v[62:63], 0, v[2:3]
	global_load_dwordx4 v[50:53], v[2:3], off
	v_add_u32_e32 v2, -4, v66
	v_ashrrev_i32_e32 v3, 31, v2
	v_lshlrev_b64 v[2:3], 9, v[2:3]
	v_lshl_add_u64 v[2:3], v[62:63], 0, v[2:3]
	global_load_dwordx4 v[38:41], v[2:3], off
	v_add_u32_e32 v2, -2, v66
	v_ashrrev_i32_e32 v3, 31, v2
	v_lshlrev_b64 v[2:3], 9, v[2:3]
	v_lshl_add_u64 v[2:3], v[62:63], 0, v[2:3]
	v_ashrrev_i32_e32 v67, 31, v66
	global_load_dwordx4 v[42:45], v[2:3], off
	v_lshlrev_b64 v[2:3], 9, v[66:67]
	v_lshl_add_u64 v[2:3], v[62:63], 0, v[2:3]
	global_load_dwordx4 v[34:37], v[2:3], off
	v_lshl_add_u64 v[2:3], s[54:55], 0, v[68:69]
	global_load_dwordx4 v[30:33], v[2:3], off offset:-256
	global_load_dwordx4 v[26:29], v[2:3], off offset:-192
	global_load_dwordx4 v[22:25], v[2:3], off offset:-128
	global_load_dwordx4 v[18:21], v[2:3], off offset:-64
	global_load_dwordx4 v[14:17], v[2:3], off
	global_load_dwordx4 v[10:13], v[2:3], off offset:64
	global_load_dwordx4 v[6:9], v[2:3], off offset:128
	s_nop 0
	global_load_dwordx4 v[2:5], v[2:3], off offset:192
	ds_read_b128 v[108:111], v73
	ds_read_b128 v[112:115], v73 offset:16640
	ds_read_b128 v[116:119], v73 offset:33280
	ds_read_b128 v[120:123], v73 offset:49920
	ds_read_b128 v[124:127], v73 offset:64
	ds_read_b128 v[128:131], v73 offset:16704
	ds_read_b128 v[132:135], v73 offset:33344
	ds_read_b128 v[136:139], v73 offset:49984
	v_lshl_add_u64 v[70:71], s[54:55], 0, v[64:65]
	s_mov_b32 s3, 0xb8c4000
	s_add_i32 s2, s2, 8
	v_lshl_add_u64 v[64:65], v[64:65], 0, s[4:5]
	v_add_u32_e32 v66, 0x800, v66
	v_lshl_add_u64 v[68:69], v[68:69], 0, s[4:5]
	s_cmp_ge_i32 s2, s0
	s_waitcnt vmcnt(15)
	s_waitcnt lgkmcnt(7)
	v_mfma_f32_16x16x32_bf16 v[78:81], v[74:77], v[108:111], 0
	ds_read_b128 v[108:111], v73 offset:128
	s_waitcnt lgkmcnt(7)
	v_mfma_f32_16x16x32_bf16 v[82:85], v[74:77], v[112:115], 0
	ds_read_b128 v[112:115], v73 offset:16768
	s_waitcnt lgkmcnt(7)
	v_mfma_f32_16x16x32_bf16 v[86:89], v[74:77], v[116:119], 0
	ds_read_b128 v[116:119], v73 offset:33408
	s_waitcnt lgkmcnt(7)
	v_mfma_f32_16x16x32_bf16 v[74:77], v[74:77], v[120:123], 0
	ds_read_b128 v[120:123], v73 offset:50048
	s_waitcnt vmcnt(14)
	s_waitcnt lgkmcnt(7)
	v_mfma_f32_16x16x32_bf16 v[90:93], v[58:61], v[124:127], v[78:81]
	ds_read_b128 v[124:127], v73 offset:192
	s_nop 2
	s_waitcnt lgkmcnt(7)
	v_mfma_f32_16x16x32_bf16 v[94:97], v[58:61], v[128:131], v[82:85]
	ds_read_b128 v[128:131], v73 offset:16832
	s_waitcnt lgkmcnt(7)
	v_mfma_f32_16x16x32_bf16 v[84:87], v[58:61], v[132:135], v[86:89]
	ds_read_b128 v[132:135], v73 offset:33472
	s_waitcnt lgkmcnt(7)
	v_mfma_f32_16x16x32_bf16 v[98:101], v[58:61], v[136:139], v[74:77]
	ds_read_b128 v[136:139], v73 offset:50112
	v_add_co_u32_e32 v58, vcc, s3, v70
	s_mov_b32 s3, 0xb8c6000
	s_nop 0
	v_addc_co_u32_e32 v59, vcc, 0, v71, vcc
	v_add_co_u32_e32 v88, vcc, s3, v70
	s_mov_b32 s3, 0xb8c8000
	s_nop 0
	v_addc_co_u32_e32 v89, vcc, 0, v71, vcc
	v_add_co_u32_e32 v102, vcc, s3, v70
	s_mov_b32 s3, 0xb8ca000
	s_nop 0
	v_addc_co_u32_e32 v103, vcc, 0, v71, vcc
	v_add_co_u32_e32 v104, vcc, s3, v70
	s_nop 7
	global_load_ushort v106, v[58:59], off
	global_load_ushort v83, v[88:89], off
	global_load_ushort v82, v[102:103], off
	v_addc_co_u32_e32 v105, vcc, 0, v71, vcc
	global_load_ushort v81, v[104:105], off
	global_load_ushort v80, v[58:59], off offset:512
	global_load_ushort v79, v[88:89], off offset:512
	global_load_ushort v78, v[102:103], off offset:512
	global_load_ushort v77, v[104:105], off offset:512
	global_load_ushort v76, v[58:59], off offset:1024
	global_load_ushort v75, v[88:89], off offset:1024
	global_load_ushort v74, v[102:103], off offset:1024
	global_load_ushort v67, v[104:105], off offset:1024
	global_load_ushort v61, v[58:59], off offset:1536
	global_load_ushort v60, v[88:89], off offset:1536
	s_nop 0
	global_load_ushort v58, v[102:103], off offset:1536
	global_load_ushort v59, v[104:105], off offset:1536
	s_waitcnt vmcnt(29)
	s_waitcnt lgkmcnt(7)
	v_mfma_f32_16x16x32_bf16 v[88:91], v[54:57], v[108:111], v[90:93]
	ds_read_b128 v[108:111], v73 offset:256
	s_mov_b32 s3, 0x13b48000
	s_waitcnt lgkmcnt(7)
	v_mfma_f32_16x16x32_bf16 v[92:95], v[54:57], v[112:115], v[94:97]
	ds_read_b128 v[112:115], v73 offset:16896
	s_waitcnt lgkmcnt(7)
	v_mfma_f32_16x16x32_bf16 v[84:87], v[54:57], v[116:119], v[84:87]
	ds_read_b128 v[116:119], v73 offset:33536
	s_waitcnt lgkmcnt(7)
	v_mfma_f32_16x16x32_bf16 v[54:57], v[54:57], v[120:123], v[98:101]
	ds_read_b128 v[120:123], v73 offset:50176
	s_nop 2
	s_waitcnt vmcnt(28)
	s_waitcnt lgkmcnt(7)
	v_mfma_f32_16x16x32_bf16 v[88:91], v[46:49], v[124:127], v[88:91]
	ds_read_b128 v[124:127], v73 offset:320
	s_waitcnt lgkmcnt(7)
	v_mfma_f32_16x16x32_bf16 v[92:95], v[46:49], v[128:131], v[92:95]
	ds_read_b128 v[128:131], v73 offset:16960
	s_waitcnt lgkmcnt(7)
	v_mfma_f32_16x16x32_bf16 v[84:87], v[46:49], v[132:135], v[84:87]
	ds_read_b128 v[132:135], v73 offset:33600
	s_waitcnt lgkmcnt(7)
	v_mfma_f32_16x16x32_bf16 v[46:49], v[46:49], v[136:139], v[54:57]
	ds_read_b128 v[136:139], v73 offset:50240
	s_nop 2
	s_waitcnt vmcnt(27)
	s_waitcnt lgkmcnt(7)
	v_mfma_f32_16x16x32_bf16 v[54:57], v[50:53], v[108:111], v[88:91]
	ds_read_b128 v[108:111], v73 offset:384
	s_nop 2
	s_waitcnt lgkmcnt(7)
	v_mfma_f32_16x16x32_bf16 v[88:91], v[50:53], v[112:115], v[92:95]
	ds_read_b128 v[112:115], v73 offset:17024
	s_nop 2
	s_waitcnt lgkmcnt(7)
	v_mfma_f32_16x16x32_bf16 v[84:87], v[50:53], v[116:119], v[84:87]
	ds_read_b128 v[116:119], v73 offset:33664
	s_waitcnt lgkmcnt(7)
	v_mfma_f32_16x16x32_bf16 v[46:49], v[50:53], v[120:123], v[46:49]
	ds_read_b128 v[120:123], v73 offset:50304
	s_waitcnt vmcnt(26)
	s_waitcnt lgkmcnt(7)
	v_mfma_f32_16x16x32_bf16 v[50:53], v[38:41], v[124:127], v[54:57]
	ds_read_b128 v[124:127], v73 offset:448
	s_nop 2
	s_waitcnt lgkmcnt(7)
	v_mfma_f32_16x16x32_bf16 v[54:57], v[38:41], v[128:131], v[88:91]
	ds_read_b128 v[128:131], v73 offset:17088
	s_nop 2
	s_waitcnt lgkmcnt(7)
	v_mfma_f32_16x16x32_bf16 v[84:87], v[38:41], v[132:135], v[84:87]
	ds_read_b128 v[132:135], v73 offset:33728
	s_waitcnt lgkmcnt(7)
	v_mfma_f32_16x16x32_bf16 v[38:41], v[38:41], v[136:139], v[46:49]
	ds_read_b128 v[136:139], v73 offset:50368
	s_nop 2
	s_waitcnt vmcnt(25)
	s_waitcnt lgkmcnt(7)
	v_mfma_f32_16x16x32_bf16 v[46:49], v[42:45], v[108:111], v[50:53]
	ds_read_b128 v[108:111], v73 offset:512
	s_nop 2
	s_waitcnt lgkmcnt(7)
	v_mfma_f32_16x16x32_bf16 v[50:53], v[42:45], v[112:115], v[54:57]
	ds_read_b128 v[112:115], v73 offset:17152
	s_nop 2
	s_waitcnt lgkmcnt(7)
	v_mfma_f32_16x16x32_bf16 v[54:57], v[42:45], v[116:119], v[84:87]
	ds_read_b128 v[116:119], v73 offset:33792
	s_nop 2
	s_waitcnt lgkmcnt(7)
	v_mfma_f32_16x16x32_bf16 v[38:41], v[42:45], v[120:123], v[38:41]
	ds_read_b128 v[120:123], v73 offset:50432
	s_waitcnt vmcnt(24)
	s_waitcnt lgkmcnt(7)
	v_mfma_f32_16x16x32_bf16 v[42:45], v[34:37], v[124:127], v[46:49]
	ds_read_b128 v[124:127], v73 offset:576
	s_nop 2
	s_waitcnt lgkmcnt(7)
	v_mfma_f32_16x16x32_bf16 v[46:49], v[34:37], v[128:131], v[50:53]
	ds_read_b128 v[128:131], v73 offset:17216
	s_nop 2
	s_waitcnt lgkmcnt(7)
	v_mfma_f32_16x16x32_bf16 v[50:53], v[34:37], v[132:135], v[54:57]
	ds_read_b128 v[132:135], v73 offset:33856
	s_nop 2
	s_waitcnt lgkmcnt(7)
	v_mfma_f32_16x16x32_bf16 v[34:37], v[34:37], v[136:139], v[38:41]
	ds_read_b128 v[136:139], v73 offset:50496
	s_nop 2
	s_waitcnt vmcnt(23)
	s_waitcnt lgkmcnt(7)
	v_mfma_f32_16x16x32_bf16 v[38:41], v[30:33], v[108:111], v[42:45]
	ds_read_b128 v[108:111], v73 offset:640
	s_nop 2
	s_waitcnt lgkmcnt(7)
	v_mfma_f32_16x16x32_bf16 v[42:45], v[30:33], v[112:115], v[46:49]
	ds_read_b128 v[112:115], v73 offset:17280
	s_nop 2
	s_waitcnt lgkmcnt(7)
	v_mfma_f32_16x16x32_bf16 v[46:49], v[30:33], v[116:119], v[50:53]
	ds_read_b128 v[116:119], v73 offset:33920
	s_nop 2
	s_waitcnt lgkmcnt(7)
	v_mfma_f32_16x16x32_bf16 v[30:33], v[30:33], v[120:123], v[34:37]
	ds_read_b128 v[120:123], v73 offset:50560
	s_nop 2
	s_waitcnt vmcnt(22)
	s_waitcnt lgkmcnt(7)
	v_mfma_f32_16x16x32_bf16 v[34:37], v[26:29], v[124:127], v[38:41]
	ds_read_b128 v[124:127], v73 offset:704
	s_nop 2
	s_waitcnt lgkmcnt(7)
	v_mfma_f32_16x16x32_bf16 v[38:41], v[26:29], v[128:131], v[42:45]
	ds_read_b128 v[128:131], v73 offset:17344
	s_nop 2
	s_waitcnt lgkmcnt(7)
	v_mfma_f32_16x16x32_bf16 v[42:45], v[26:29], v[132:135], v[46:49]
	ds_read_b128 v[132:135], v73 offset:33984
	s_nop 2
	s_waitcnt lgkmcnt(7)
	v_mfma_f32_16x16x32_bf16 v[26:29], v[26:29], v[136:139], v[30:33]
	ds_read_b128 v[136:139], v73 offset:50624
	s_nop 2
	s_waitcnt vmcnt(21)
	s_waitcnt lgkmcnt(7)
	v_mfma_f32_16x16x32_bf16 v[30:33], v[22:25], v[108:111], v[34:37]
	ds_read_b128 v[108:111], v73 offset:768
	s_nop 2
	s_waitcnt lgkmcnt(7)
	v_mfma_f32_16x16x32_bf16 v[34:37], v[22:25], v[112:115], v[38:41]
	ds_read_b128 v[112:115], v73 offset:17408
	s_nop 2
	s_waitcnt lgkmcnt(7)
	v_mfma_f32_16x16x32_bf16 v[38:41], v[22:25], v[116:119], v[42:45]
	ds_read_b128 v[116:119], v73 offset:34048
	s_nop 2
	s_waitcnt lgkmcnt(7)
	v_mfma_f32_16x16x32_bf16 v[22:25], v[22:25], v[120:123], v[26:29]
	ds_read_b128 v[120:123], v73 offset:50688
	s_nop 2
	s_waitcnt vmcnt(20)
	s_waitcnt lgkmcnt(7)
	v_mfma_f32_16x16x32_bf16 v[26:29], v[18:21], v[124:127], v[30:33]
	ds_read_b128 v[124:127], v73 offset:832
	s_nop 2
	s_waitcnt lgkmcnt(7)
	v_mfma_f32_16x16x32_bf16 v[30:33], v[18:21], v[128:131], v[34:37]
	ds_read_b128 v[128:131], v73 offset:17472
	s_nop 2
	s_waitcnt lgkmcnt(7)
	v_mfma_f32_16x16x32_bf16 v[34:37], v[18:21], v[132:135], v[38:41]
	ds_read_b128 v[132:135], v73 offset:34112
	s_nop 2
	s_waitcnt lgkmcnt(7)
	v_mfma_f32_16x16x32_bf16 v[18:21], v[18:21], v[136:139], v[22:25]
	ds_read_b128 v[136:139], v73 offset:50752
	s_nop 2
	s_waitcnt vmcnt(19)
	s_waitcnt lgkmcnt(7)
	v_mfma_f32_16x16x32_bf16 v[22:25], v[14:17], v[108:111], v[26:29]
	ds_read_b128 v[108:111], v73 offset:896
	s_nop 2
	s_waitcnt lgkmcnt(7)
	v_mfma_f32_16x16x32_bf16 v[26:29], v[14:17], v[112:115], v[30:33]
	ds_read_b128 v[112:115], v73 offset:17536
	s_nop 2
	s_waitcnt lgkmcnt(7)
	v_mfma_f32_16x16x32_bf16 v[30:33], v[14:17], v[116:119], v[34:37]
	ds_read_b128 v[116:119], v73 offset:34176
	s_nop 2
	s_waitcnt lgkmcnt(7)
	v_mfma_f32_16x16x32_bf16 v[14:17], v[14:17], v[120:123], v[18:21]
	ds_read_b128 v[120:123], v73 offset:50816
	s_nop 2
	s_waitcnt vmcnt(18)
	s_waitcnt lgkmcnt(7)
	v_mfma_f32_16x16x32_bf16 v[18:21], v[10:13], v[124:127], v[22:25]
	ds_read_b128 v[124:127], v73 offset:960
	s_nop 2
	s_waitcnt lgkmcnt(7)
	v_mfma_f32_16x16x32_bf16 v[22:25], v[10:13], v[128:131], v[26:29]
	ds_read_b128 v[128:131], v73 offset:17600
	s_nop 2
	s_waitcnt lgkmcnt(7)
	v_mfma_f32_16x16x32_bf16 v[26:29], v[10:13], v[132:135], v[30:33]
	ds_read_b128 v[132:135], v73 offset:34240
	s_nop 2
	s_waitcnt lgkmcnt(7)
	v_mfma_f32_16x16x32_bf16 v[10:13], v[10:13], v[136:139], v[14:17]
	ds_read_b128 v[136:139], v73 offset:50880
	s_nop 2
	s_waitcnt vmcnt(17)
	s_waitcnt lgkmcnt(7)
	v_mfma_f32_16x16x32_bf16 v[14:17], v[6:9], v[108:111], v[18:21]
	s_nop 2
	s_waitcnt lgkmcnt(6)
	v_mfma_f32_16x16x32_bf16 v[18:21], v[6:9], v[112:115], v[22:25]
	s_nop 2
	s_waitcnt lgkmcnt(5)
	v_mfma_f32_16x16x32_bf16 v[22:25], v[6:9], v[116:119], v[26:29]
	s_nop 2
	s_waitcnt lgkmcnt(4)
	v_mfma_f32_16x16x32_bf16 v[26:29], v[6:9], v[120:123], v[10:13]
	s_waitcnt vmcnt(16)
	s_waitcnt lgkmcnt(3)
	v_mfma_f32_16x16x32_bf16 v[30:33], v[2:5], v[124:127], v[14:17]
	s_nop 1
	s_waitcnt lgkmcnt(2)
	v_mfma_f32_16x16x32_bf16 v[10:13], v[2:5], v[128:131], v[18:21]
	s_waitcnt lgkmcnt(1)
	v_mfma_f32_16x16x32_bf16 v[6:9], v[2:5], v[132:135], v[22:25]
	s_waitcnt lgkmcnt(0)
	v_mfma_f32_16x16x32_bf16 v[2:5], v[2:5], v[136:139], v[26:29]
	s_waitcnt vmcnt(15)
	v_lshlrev_b32_e32 v14, 16, v106
	v_fma_f32 v14, v72, v14, v30
	v_mul_f32_e32 v15, 0x3d372713, v14
	v_mul_f32_e32 v15, v14, v15
	v_fma_f32 v15, v14, v15, v14
	v_mul_f32_e32 v15, 0x3f4c422a, v15
	v_add_f32_e32 v15, v15, v15
	v_mul_f32_e32 v15, 0x3fb8aa3b, v15
	v_exp_f32_e32 v15, v15
	v_mul_f32_e32 v14, 0.5, v14
	v_add_f32_e32 v15, 1.0, v15
	v_rcp_f32_e32 v15, v15
	s_nop 0
	v_fma_f32 v15, v15, -2.0, 1.0
	v_add_f32_e32 v15, 1.0, v15
	v_mul_f32_e32 v14, v14, v15
	v_cvt_pk_bf16_f32 v16, v14, s0
	v_add_co_u32_e32 v14, vcc, s3, v70
	s_mov_b32 s3, 0x13b4a000
	s_nop 0
	v_addc_co_u32_e32 v15, vcc, 0, v71, vcc
	global_store_short v[14:15], v16, off offset:256
	s_waitcnt vmcnt(15)
	v_lshlrev_b32_e32 v16, 16, v83
	v_fma_f32 v16, v72, v16, v31
	v_mul_f32_e32 v17, 0x3d372713, v16
	v_mul_f32_e32 v17, v16, v17
	v_fma_f32 v17, v16, v17, v16
	v_mul_f32_e32 v17, 0x3f4c422a, v17
	v_add_f32_e32 v17, v17, v17
	v_mul_f32_e32 v17, 0x3fb8aa3b, v17
	v_exp_f32_e32 v17, v17
	v_mul_f32_e32 v16, 0.5, v16
	v_add_f32_e32 v17, 1.0, v17
	v_rcp_f32_e32 v17, v17
	s_nop 0
	v_fma_f32 v17, v17, -2.0, 1.0
	v_add_f32_e32 v17, 1.0, v17
	v_mul_f32_e32 v16, v16, v17
	v_cvt_pk_bf16_f32 v18, v16, s0
	v_add_co_u32_e32 v16, vcc, s3, v70
	s_mov_b32 s3, 0x13b4c000
	s_nop 0
	v_addc_co_u32_e32 v17, vcc, 0, v71, vcc
	global_store_short v[16:17], v18, off offset:256
	s_waitcnt vmcnt(15)
	v_lshlrev_b32_e32 v18, 16, v82
	v_fma_f32 v18, v72, v18, v32
	v_mul_f32_e32 v19, 0x3d372713, v18
	v_mul_f32_e32 v19, v18, v19
	v_fma_f32 v19, v18, v19, v18
	v_mul_f32_e32 v19, 0x3f4c422a, v19
	v_add_f32_e32 v19, v19, v19
	v_mul_f32_e32 v19, 0x3fb8aa3b, v19
	v_exp_f32_e32 v19, v19
	v_mul_f32_e32 v18, 0.5, v18
	v_add_f32_e32 v19, 1.0, v19
	v_rcp_f32_e32 v19, v19
	s_nop 0
	v_fma_f32 v19, v19, -2.0, 1.0
	v_add_f32_e32 v19, 1.0, v19
	v_mul_f32_e32 v18, v18, v19
	v_cvt_pk_bf16_f32 v20, v18, s0
	v_add_co_u32_e32 v18, vcc, s3, v70
	s_mov_b32 s3, 0x13b4e000
	s_nop 0
	v_addc_co_u32_e32 v19, vcc, 0, v71, vcc
	global_store_short v[18:19], v20, off offset:256
	s_waitcnt vmcnt(15)
	v_lshlrev_b32_e32 v20, 16, v81
	v_fmac_f32_e32 v33, v72, v20
	v_mul_f32_e32 v20, 0x3d372713, v33
	v_mul_f32_e32 v20, v33, v20
	v_fma_f32 v20, v33, v20, v33
	v_mul_f32_e32 v20, 0x3f4c422a, v20
	v_add_f32_e32 v20, v20, v20
	v_mul_f32_e32 v20, 0x3fb8aa3b, v20
	v_exp_f32_e32 v20, v20
	v_mul_f32_e32 v21, 0.5, v33
	v_add_f32_e32 v20, 1.0, v20
	v_rcp_f32_e32 v20, v20
	s_nop 0
	v_fma_f32 v20, v20, -2.0, 1.0
	v_add_f32_e32 v20, 1.0, v20
	v_mul_f32_e32 v20, v21, v20
	v_cvt_pk_bf16_f32 v22, v20, s0
	v_add_co_u32_e32 v20, vcc, s3, v70
	s_nop 1
	v_addc_co_u32_e32 v21, vcc, 0, v71, vcc
	global_store_short v[20:21], v22, off offset:256
	s_waitcnt vmcnt(15)
	v_lshlrev_b32_e32 v22, 16, v80
	v_fma_f32 v10, v72, v22, v10
	v_mul_f32_e32 v22, 0x3d372713, v10
	v_mul_f32_e32 v22, v10, v22
	v_fma_f32 v22, v10, v22, v10
	v_mul_f32_e32 v22, 0x3f4c422a, v22
	v_add_f32_e32 v22, v22, v22
	v_mul_f32_e32 v22, 0x3fb8aa3b, v22
	v_exp_f32_e32 v22, v22
	v_mul_f32_e32 v10, 0.5, v10
	v_add_f32_e32 v22, 1.0, v22
	v_rcp_f32_e32 v22, v22
	s_nop 0
	v_fma_f32 v22, v22, -2.0, 1.0
	v_add_f32_e32 v22, 1.0, v22
	v_mul_f32_e32 v10, v10, v22
	v_cvt_pk_bf16_f32 v10, v10, s0
	global_store_short v[14:15], v10, off offset:768
	s_waitcnt vmcnt(15)
	v_lshlrev_b32_e32 v10, 16, v79
	v_fma_f32 v10, v72, v10, v11
	v_mul_f32_e32 v11, 0x3d372713, v10
	v_mul_f32_e32 v11, v10, v11
	v_fma_f32 v11, v10, v11, v10
	v_mul_f32_e32 v11, 0x3f4c422a, v11
	v_add_f32_e32 v11, v11, v11
	v_mul_f32_e32 v11, 0x3fb8aa3b, v11
	v_exp_f32_e32 v11, v11
	v_mul_f32_e32 v10, 0.5, v10
	v_add_f32_e32 v11, 1.0, v11
	v_rcp_f32_e32 v11, v11
	s_nop 0
	v_fma_f32 v11, v11, -2.0, 1.0
	v_add_f32_e32 v11, 1.0, v11
	v_mul_f32_e32 v10, v10, v11
	v_cvt_pk_bf16_f32 v10, v10, s0
	global_store_short v[16:17], v10, off offset:768
	s_waitcnt vmcnt(15)
	v_lshlrev_b32_e32 v10, 16, v78
	v_fma_f32 v10, v72, v10, v12
	v_mul_f32_e32 v11, 0x3d372713, v10
	v_mul_f32_e32 v11, v10, v11
	v_fma_f32 v11, v10, v11, v10
	v_mul_f32_e32 v11, 0x3f4c422a, v11
	v_add_f32_e32 v11, v11, v11
	v_mul_f32_e32 v11, 0x3fb8aa3b, v11
	v_exp_f32_e32 v11, v11
	v_mul_f32_e32 v10, 0.5, v10
	v_add_f32_e32 v11, 1.0, v11
	v_rcp_f32_e32 v11, v11
	s_nop 0
	v_fma_f32 v11, v11, -2.0, 1.0
	v_add_f32_e32 v11, 1.0, v11
	v_mul_f32_e32 v10, v10, v11
	v_cvt_pk_bf16_f32 v10, v10, s0
	global_store_short v[18:19], v10, off offset:768
	s_waitcnt vmcnt(15)
	v_lshlrev_b32_e32 v10, 16, v77
	v_fmac_f32_e32 v13, v72, v10
	v_mul_f32_e32 v10, 0x3d372713, v13
	v_mul_f32_e32 v10, v13, v10
	v_fma_f32 v10, v13, v10, v13
	v_mul_f32_e32 v10, 0x3f4c422a, v10
	v_add_f32_e32 v10, v10, v10
	v_mul_f32_e32 v10, 0x3fb8aa3b, v10
	v_exp_f32_e32 v10, v10
	v_mul_f32_e32 v11, 0.5, v13
	v_add_f32_e32 v10, 1.0, v10
	v_rcp_f32_e32 v10, v10
	s_nop 0
	v_fma_f32 v10, v10, -2.0, 1.0
	v_add_f32_e32 v10, 1.0, v10
	v_mul_f32_e32 v10, v11, v10
	v_cvt_pk_bf16_f32 v10, v10, s0
	global_store_short v[20:21], v10, off offset:768
	s_waitcnt vmcnt(15)
	v_lshlrev_b32_e32 v10, 16, v76
	v_fma_f32 v6, v72, v10, v6
	v_mul_f32_e32 v10, 0x3d372713, v6
	v_mul_f32_e32 v10, v6, v10
	v_fma_f32 v10, v6, v10, v6
	v_mul_f32_e32 v10, 0x3f4c422a, v10
	v_add_f32_e32 v10, v10, v10
	v_mul_f32_e32 v10, 0x3fb8aa3b, v10
	v_exp_f32_e32 v10, v10
	v_mul_f32_e32 v6, 0.5, v6
	v_add_f32_e32 v10, 1.0, v10
	v_rcp_f32_e32 v10, v10
	s_nop 0
	v_fma_f32 v10, v10, -2.0, 1.0
	v_add_f32_e32 v10, 1.0, v10
	v_mul_f32_e32 v6, v6, v10
	v_cvt_pk_bf16_f32 v6, v6, s0
	global_store_short v[14:15], v6, off offset:1280
	s_waitcnt vmcnt(15)
	v_lshlrev_b32_e32 v6, 16, v75
	v_fma_f32 v6, v72, v6, v7
	v_mul_f32_e32 v7, 0x3d372713, v6
	v_mul_f32_e32 v7, v6, v7
	v_fma_f32 v7, v6, v7, v6
	v_mul_f32_e32 v7, 0x3f4c422a, v7
	v_add_f32_e32 v7, v7, v7
	v_mul_f32_e32 v7, 0x3fb8aa3b, v7
	v_exp_f32_e32 v7, v7
	v_mul_f32_e32 v6, 0.5, v6
	v_add_f32_e32 v7, 1.0, v7
	v_rcp_f32_e32 v7, v7
	s_nop 0
	v_fma_f32 v7, v7, -2.0, 1.0
	v_add_f32_e32 v7, 1.0, v7
	v_mul_f32_e32 v6, v6, v7
	v_cvt_pk_bf16_f32 v6, v6, s0
	global_store_short v[16:17], v6, off offset:1280
	s_waitcnt vmcnt(15)
	v_lshlrev_b32_e32 v6, 16, v74
	v_fma_f32 v6, v72, v6, v8
	v_mul_f32_e32 v7, 0x3d372713, v6
	v_mul_f32_e32 v7, v6, v7
	v_fma_f32 v7, v6, v7, v6
	v_mul_f32_e32 v7, 0x3f4c422a, v7
	v_add_f32_e32 v7, v7, v7
	v_mul_f32_e32 v7, 0x3fb8aa3b, v7
	v_exp_f32_e32 v7, v7
	v_mul_f32_e32 v6, 0.5, v6
	v_add_f32_e32 v7, 1.0, v7
	v_rcp_f32_e32 v7, v7
	s_nop 0
	v_fma_f32 v7, v7, -2.0, 1.0
	v_add_f32_e32 v7, 1.0, v7
	v_mul_f32_e32 v6, v6, v7
	v_cvt_pk_bf16_f32 v6, v6, s0
	global_store_short v[18:19], v6, off offset:1280
	s_waitcnt vmcnt(15)
	v_lshlrev_b32_e32 v6, 16, v67
	v_fmac_f32_e32 v9, v72, v6
	v_mul_f32_e32 v6, 0x3d372713, v9
	v_mul_f32_e32 v6, v9, v6
	v_fma_f32 v6, v9, v6, v9
	v_mul_f32_e32 v6, 0x3f4c422a, v6
	v_add_f32_e32 v6, v6, v6
	v_mul_f32_e32 v6, 0x3fb8aa3b, v6
	v_exp_f32_e32 v6, v6
	v_mul_f32_e32 v7, 0.5, v9
	v_add_f32_e32 v6, 1.0, v6
	v_rcp_f32_e32 v6, v6
	s_nop 0
	v_fma_f32 v6, v6, -2.0, 1.0
	v_add_f32_e32 v6, 1.0, v6
	v_mul_f32_e32 v6, v7, v6
	v_cvt_pk_bf16_f32 v6, v6, s0
	global_store_short v[20:21], v6, off offset:1280
	s_waitcnt vmcnt(15)
	v_lshlrev_b32_e32 v6, 16, v61
	v_fma_f32 v2, v72, v6, v2
	v_mul_f32_e32 v6, 0x3d372713, v2
	v_mul_f32_e32 v6, v2, v6
	v_fma_f32 v6, v2, v6, v2
	v_mul_f32_e32 v6, 0x3f4c422a, v6
	v_add_f32_e32 v6, v6, v6
	v_mul_f32_e32 v6, 0x3fb8aa3b, v6
	v_exp_f32_e32 v6, v6
	v_mul_f32_e32 v2, 0.5, v2
	v_add_f32_e32 v6, 1.0, v6
	v_rcp_f32_e32 v6, v6
	s_nop 0
	v_fma_f32 v6, v6, -2.0, 1.0
	v_add_f32_e32 v6, 1.0, v6
	v_mul_f32_e32 v2, v2, v6
	v_cvt_pk_bf16_f32 v2, v2, s0
	global_store_short v[14:15], v2, off offset:1792
	s_waitcnt vmcnt(15)
	v_lshlrev_b32_e32 v2, 16, v60
	v_fma_f32 v2, v72, v2, v3
	v_mul_f32_e32 v3, 0x3d372713, v2
	v_mul_f32_e32 v3, v2, v3
	v_fma_f32 v3, v2, v3, v2
	v_mul_f32_e32 v3, 0x3f4c422a, v3
	v_add_f32_e32 v3, v3, v3
	v_mul_f32_e32 v3, 0x3fb8aa3b, v3
	v_exp_f32_e32 v3, v3
	v_mul_f32_e32 v2, 0.5, v2
	v_add_f32_e32 v3, 1.0, v3
	v_rcp_f32_e32 v3, v3
	s_nop 0
	v_fma_f32 v3, v3, -2.0, 1.0
	v_add_f32_e32 v3, 1.0, v3
	v_mul_f32_e32 v2, v2, v3
	v_cvt_pk_bf16_f32 v2, v2, s0
	global_store_short v[16:17], v2, off offset:1792
	s_waitcnt vmcnt(15)
	v_lshlrev_b32_e32 v2, 16, v58
	v_fma_f32 v2, v72, v2, v4
	v_mul_f32_e32 v3, 0x3d372713, v2
	v_mul_f32_e32 v3, v2, v3
	v_fma_f32 v3, v2, v3, v2
	v_mul_f32_e32 v3, 0x3f4c422a, v3
	v_add_f32_e32 v3, v3, v3
	v_mul_f32_e32 v3, 0x3fb8aa3b, v3
	v_exp_f32_e32 v3, v3
	v_mul_f32_e32 v2, 0.5, v2
	v_add_f32_e32 v3, 1.0, v3
	v_rcp_f32_e32 v3, v3
	s_nop 0
	v_fma_f32 v3, v3, -2.0, 1.0
	v_add_f32_e32 v3, 1.0, v3
	v_mul_f32_e32 v2, v2, v3
	v_cvt_pk_bf16_f32 v2, v2, s0
	global_store_short v[18:19], v2, off offset:1792
	s_waitcnt vmcnt(15)
	v_lshlrev_b32_e32 v2, 16, v59
	v_fmac_f32_e32 v5, v72, v2
	v_mul_f32_e32 v2, 0x3d372713, v5
	v_mul_f32_e32 v2, v5, v2
	v_fma_f32 v2, v5, v2, v5
	v_mul_f32_e32 v2, 0x3f4c422a, v2
	v_add_f32_e32 v2, v2, v2
	v_mul_f32_e32 v2, 0x3fb8aa3b, v2
	v_exp_f32_e32 v2, v2
	v_mul_f32_e32 v3, 0.5, v5
	v_add_f32_e32 v2, 1.0, v2
	v_rcp_f32_e32 v2, v2
	s_nop 0
	v_fma_f32 v2, v2, -2.0, 1.0
	v_add_f32_e32 v2, 1.0, v2
	v_mul_f32_e32 v2, v3, v2
	v_cvt_pk_bf16_f32 v2, v2, s0
	global_store_short v[20:21], v2, off offset:1792
	s_cbranch_scc0 .LBB0_960
